# seam 2/3 waits: polls and L1 invalidate issued before the ple tile's store drain (overlapped); rest as v166
# baseline (speedup 1.0000x reference)
; __device__ __forceinline__ u32x4 pack8(const f32x4 a, const f32x4 b) { u32x4 w; w.x = cvt_pk_bf16(a[0], a[1]); w.y = cvt_pk_bf16(a[2], a[3]); w.z = cvt_pk_bf16(b[0], b[1]); w.w = cvt_pk_bf16(b[2], b[3]); return w; }
; __device__ __forceinline__ int lane_id() { int l; asm volatile("v_mbcnt_lo_u32_b32 %0, -1, 0\n\tv_mbcnt_hi_u32_b32 %0, -1, %0" : "=v"(l)); return l; }
; __device__ __forceinline__ unsigned xb_ld(unsigned* p)              { return __hip_atomic_load(p, __ATOMIC_RELAXED, __HIP_MEMORY_SCOPE_AGENT); }
; #define XB_SPIN(cond, bar) do { unsigned _sp = 0; while (cond) { __builtin_amdgcn_s_sleep(1); \
;     if ((++_sp & 255u) == 0u) { if (xb_ld(&(bar)[XB_TMO])) break; if (_sp > XB_SPIN_CAP) { atomicAdd(&(bar)[XB_TMO], 1u); break; } } } } while (0)
;     __device__ __forceinline__ void operator()(const f32x4 (&acc)[2][2][4][2], const Unit& u, int wr, int wc, int fr, int fq) const {
;         const int row0 = u.pm * BM + wr * 64 + fr, col0 = u.pn * BM + wc * 32 + 8 * fq;
; #pragma unroll
;         for (int ai = 0; ai < 2; ++ai)
; #pragma unroll
;             for (int m = 0; m < 4; ++m) { bf16_t* rowp = O + (size_t)(row0 + ai * HALF + m * 16) * ldc + col0;
; #pragma unroll
;                 for (int bj = 0; bj < 2; ++bj) *(u32x4*)(rowp + bj * HALF) = pack8(acc[ai][bj][m][0], acc[ai][bj][m][1]); }
; __device__ __forceinline__ void xcd_wait2(const XcdBarrier& b, unsigned use, unsigned* obar, unsigned ouse) {
;     if (b.w0 != 0 && lane_id() == 0) {
;         unsigned* bar = b.bar;
;         XB_SPIN(xb_ld(&obar[XB_TOPGEN]) <= ouse, bar);
;         XB_SPIN(xb_ld(&bar[XB_TOPGEN]) <= use, bar);
;         __builtin_amdgcn_fence(__ATOMIC_ACQUIRE, "agent");
;         asm volatile("s_waitcnt vmcnt(0)" ::: "memory");
;     }
;     __syncthreads();
.LBB0_486:
	s_add_u32 s0, s34, s46
	s_addc_u32 s1, s35, 0
	s_add_u32 s2, s0, 0x13200000
	s_addc_u32 s3, s1, 0
	v_lshl_add_u32 v130, s12, 8, v129
	s_lshl_b32 s0, s91, 8
	s_or_b32 s97, s54, s0
	v_ashrrev_i32_e32 v131, 31, v130
	v_or_b32_e32 v132, s97, v128
	v_lshlrev_b64 v[128:129], 12, v[130:131]
	v_lshl_add_u64 v[128:129], s[2:3], 0, v[128:129]
	v_lshlrev_b32_e32 v168, 1, v132
	v_mov_b32_e32 v169, 0
	v_lshl_add_u64 v[128:129], v[128:129], 0, v[168:169]
	v_cvt_pk_bf16_f32 v120, v120, v121
	v_cvt_pk_bf16_f32 v121, v122, v123
	v_cvt_pk_bf16_f32 v122, v112, v113
	v_cvt_pk_bf16_f32 v123, v114, v115
	global_store_dwordx4 v[128:129], v[120:123], off
	v_cvt_pk_bf16_f32 v112, v124, v125
	v_cvt_pk_bf16_f32 v113, v126, v127
	v_cvt_pk_bf16_f32 v114, v116, v117
	v_cvt_pk_bf16_f32 v115, v118, v119
	global_store_dwordx4 v[128:129], v[112:115], off offset:256
	v_cvt_pk_bf16_f32 v104, v104, v105
	v_cvt_pk_bf16_f32 v105, v106, v107
	v_cvt_pk_bf16_f32 v106, v96, v97
	v_cvt_pk_bf16_f32 v107, v98, v99
	v_writelane_b32 v254, s0, 17
	s_nop 0
	v_or_b32_e32 v112, 16, v130
	v_ashrrev_i32_e32 v113, 31, v112
	v_lshlrev_b64 v[112:113], 12, v[112:113]
	v_lshl_add_u64 v[112:113], s[2:3], 0, v[112:113]
	v_lshl_add_u64 v[112:113], v[112:113], 0, v[168:169]
	global_store_dwordx4 v[112:113], v[104:107], off
	v_cvt_pk_bf16_f32 v96, v108, v109
	v_cvt_pk_bf16_f32 v97, v110, v111
	v_cvt_pk_bf16_f32 v98, v100, v101
	v_cvt_pk_bf16_f32 v99, v102, v103
	global_store_dwordx4 v[112:113], v[96:99], off offset:256
	v_cvt_pk_bf16_f32 v88, v88, v89
	v_cvt_pk_bf16_f32 v89, v90, v91
	v_cvt_pk_bf16_f32 v90, v80, v81
	v_cvt_pk_bf16_f32 v91, v82, v83
	s_mov_b32 s0, 0x80000
	s_nop 0
	v_or_b32_e32 v96, 32, v130
	v_ashrrev_i32_e32 v97, 31, v96
	v_lshlrev_b64 v[96:97], 12, v[96:97]
	v_lshl_add_u64 v[96:97], s[2:3], 0, v[96:97]
	v_lshl_add_u64 v[96:97], v[96:97], 0, v[168:169]
	global_store_dwordx4 v[96:97], v[88:91], off
	v_cvt_pk_bf16_f32 v80, v92, v93
	v_cvt_pk_bf16_f32 v81, v94, v95
	v_cvt_pk_bf16_f32 v82, v84, v85
	v_cvt_pk_bf16_f32 v83, v86, v87
	global_store_dwordx4 v[96:97], v[80:83], off offset:256
	v_cvt_pk_bf16_f32 v56, v56, v57
	v_cvt_pk_bf16_f32 v57, v58, v59
	v_cvt_pk_bf16_f32 v58, v48, v49
	v_cvt_pk_bf16_f32 v59, v50, v51
	s_mov_b64 s[36:37], 0x80000
	s_nop 0
	v_or_b32_e32 v80, 48, v130
	v_ashrrev_i32_e32 v81, 31, v80
	v_lshlrev_b64 v[80:81], 12, v[80:81]
	v_lshl_add_u64 v[80:81], s[2:3], 0, v[80:81]
	v_lshl_add_u64 v[80:81], v[80:81], 0, v[168:169]
	global_store_dwordx4 v[80:81], v[56:59], off
	v_cvt_pk_bf16_f32 v48, v60, v61
	v_cvt_pk_bf16_f32 v49, v62, v63
	v_cvt_pk_bf16_f32 v50, v52, v53
	v_cvt_pk_bf16_f32 v51, v54, v55
	v_add_co_u32_e32 v54, vcc, s0, v128
	global_store_dwordx4 v[80:81], v[48:51], off offset:256
	s_nop 0
	v_addc_co_u32_e32 v55, vcc, 0, v129, vcc
	v_cvt_pk_bf16_f32 v48, v76, v77
	v_cvt_pk_bf16_f32 v49, v78, v79
	v_lshl_add_u64 v[52:53], v[128:129], 0, s[36:37]
	v_cvt_pk_bf16_f32 v50, v68, v69
	v_cvt_pk_bf16_f32 v51, v70, v71
	global_store_dwordx4 v[54:55], v[48:51], off
	s_mov_b64 s[0:1], 0x90000
	s_nop 0
	v_cvt_pk_bf16_f32 v48, v72, v73
	v_cvt_pk_bf16_f32 v49, v74, v75
	v_cvt_pk_bf16_f32 v50, v64, v65
	v_cvt_pk_bf16_f32 v51, v66, v67
	global_store_dwordx4 v[52:53], v[48:51], off offset:256
	v_cvt_pk_bf16_f32 v44, v44, v45
	v_cvt_pk_bf16_f32 v45, v46, v47
	v_cvt_pk_bf16_f32 v46, v36, v37
	v_cvt_pk_bf16_f32 v47, v38, v39
	s_nop 1
	v_lshl_add_u64 v[48:49], v[128:129], 0, s[0:1]
	s_mov_b32 s0, 0x90000
	v_add_co_u32_e32 v36, vcc, s0, v128
	s_mov_b64 s[0:1], 0xa0000
	s_nop 0
	v_addc_co_u32_e32 v37, vcc, 0, v129, vcc
	global_store_dwordx4 v[36:37], v[44:47], off
	v_cvt_pk_bf16_f32 v36, v40, v41
	v_cvt_pk_bf16_f32 v37, v42, v43
	v_cvt_pk_bf16_f32 v38, v32, v33
	v_lshl_add_u64 v[32:33], v[128:129], 0, s[0:1]
	s_mov_b32 s0, 0xa0000
	v_cvt_pk_bf16_f32 v39, v34, v35
	global_store_dwordx4 v[48:49], v[36:39], off offset:256
	v_cvt_pk_bf16_f32 v28, v28, v29
	v_cvt_pk_bf16_f32 v29, v30, v31
	v_cvt_pk_bf16_f32 v30, v20, v21
	v_add_co_u32_e32 v20, vcc, s0, v128
	s_mov_b64 s[0:1], 0xb0000
	s_nop 0
	v_addc_co_u32_e32 v21, vcc, 0, v129, vcc
	v_cvt_pk_bf16_f32 v31, v22, v23
	global_store_dwordx4 v[20:21], v[28:31], off
	v_cvt_pk_bf16_f32 v20, v24, v25
	v_cvt_pk_bf16_f32 v21, v26, v27
	v_cvt_pk_bf16_f32 v22, v16, v17
	v_lshl_add_u64 v[16:17], v[128:129], 0, s[0:1]
	s_mov_b32 s0, 0xb0000
	v_cvt_pk_bf16_f32 v23, v18, v19
	global_store_dwordx4 v[32:33], v[20:23], off offset:256
	v_cvt_pk_bf16_f32 v12, v12, v13
	v_cvt_pk_bf16_f32 v13, v14, v15
	v_cvt_pk_bf16_f32 v14, v4, v5
	v_add_co_u32_e32 v4, vcc, s0, v128
	v_cvt_pk_bf16_f32 v15, v6, v7
	s_nop 1
	v_addc_co_u32_e32 v5, vcc, 0, v129, vcc
	global_store_dwordx4 v[4:5], v[12:15], off
	v_cvt_pk_bf16_f32 v4, v8, v9
	v_cvt_pk_bf16_f32 v5, v10, v11
	v_cvt_pk_bf16_f32 v6, v0, v1
	v_cvt_pk_bf16_f32 v7, v2, v3
	global_store_dwordx4 v[16:17], v[4:7], off offset:256
	s_and_b64 vcc, exec, s[94:95]
	s_cbranch_vccnz .Lfw2_skip
	s_mov_b64 s[42:43], exec
	v_mbcnt_lo_u32_b32 v0, -1, 0
	v_mbcnt_hi_u32_b32 v0, -1, v0
	v_cmp_eq_u32_e32 vcc, 0, v0
	s_and_b64 exec, exec, vcc
	v_readlane_b32 s40, v254, 0
	s_xor_b32 s40, s40, 1
	s_mulk_i32 s40, 0x3600
	s_add_u32 s40, s34, s40
	s_addc_u32 s41, s35, 0
	v_mov_b32_e32 v0, 0x17000
	global_load_dword v2, v0, s[40:41] offset:1280 sc1
	v_readlane_b32 s38, v254, 19
	v_readlane_b32 s39, v254, 21
	s_add_i32 s38, s38, s39
	s_lshl_b32 s38, s38, 7
	s_add_u32 s38, s38, 0x7000
	v_mov_b32_e32 v0, s38
	global_load_dword v1, v0, s[52:53] sc1
	buffer_inv sc1
	s_mov_b64 exec, s[42:43]
.Lfw2_skip:
	s_waitcnt vmcnt(0)
	s_and_b64 vcc, exec, s[94:95]
	s_barrier
	s_cbranch_vccnz .LBB0_516
	v_mbcnt_lo_u32_b32 v0, -1, 0
	v_mbcnt_hi_u32_b32 v0, -1, v0
	s_nop 0
	v_cmp_eq_u32_e32 vcc, 0, v0
	s_and_saveexec_b64 s[14:15], vcc
	s_cbranch_execz .LBB0_515
	v_cmp_lt_u32_e32 vcc, 1, v2
	v_cmp_lt_u32_e64 s[38:39], 7, v1
	s_and_b64 vcc, vcc, s[38:39]
	s_cbranch_vccnz .LBB0_515
	v_readlane_b32 s0, v254, 0
	s_xor_b32 s0, s0, 1
	s_mulk_i32 s0, 0x3600
	s_add_u32 s0, s34, s0
	s_addc_u32 s1, s35, 0
	v_mov_b32_e32 v0, 0x17000
	global_load_dword v0, v0, s[0:1] offset:1280 sc1
	s_add_u32 s38, s0, 0x17500
	s_addc_u32 s39, s1, 0
	s_mov_b32 s0, 1
	s_waitcnt vmcnt(0)
	v_cmp_lt_u32_e32 vcc, 1, v0
	s_cbranch_vccnz .LBB0_501
	v_mov_b32_e32 v0, 0
	s_branch .LBB0_491

; __device__ __forceinline__ u32x4 pack8(const f32x4 a, const f32x4 b) { u32x4 w; w.x = cvt_pk_bf16(a[0], a[1]); w.y = cvt_pk_bf16(a[2], a[3]); w.z = cvt_pk_bf16(b[0], b[1]); w.w = cvt_pk_bf16(b[2], b[3]); return w; }
; __device__ __forceinline__ int lane_id() { int l; asm volatile("v_mbcnt_lo_u32_b32 %0, -1, 0\n\tv_mbcnt_hi_u32_b32 %0, -1, %0" : "=v"(l)); return l; }
; __device__ __forceinline__ unsigned xb_ld(unsigned* p)              { return __hip_atomic_load(p, __ATOMIC_RELAXED, __HIP_MEMORY_SCOPE_AGENT); }
; #define XB_SPIN(cond, bar) do { unsigned _sp = 0; while (cond) { __builtin_amdgcn_s_sleep(1); \
;     if ((++_sp & 255u) == 0u) { if (xb_ld(&(bar)[XB_TMO])) break; if (_sp > XB_SPIN_CAP) { atomicAdd(&(bar)[XB_TMO], 1u); break; } } } } while (0)
;     __device__ __forceinline__ void operator()(const f32x4 (&acc)[2][2][4][2], const Unit& u, int wr, int wc, int fr, int fq) const {
;         const int row0 = u.pm * BM + wr * 64 + fr, col0 = u.pn * BM + wc * 32 + 8 * fq;
; #pragma unroll
;         for (int ai = 0; ai < 2; ++ai)
; #pragma unroll
;             for (int m = 0; m < 4; ++m) { bf16_t* rowp = O + (size_t)(row0 + ai * HALF + m * 16) * ldc + col0;
; #pragma unroll
;                 for (int bj = 0; bj < 2; ++bj) *(u32x4*)(rowp + bj * HALF) = pack8(acc[ai][bj][m][0], acc[ai][bj][m][1]); }
; __device__ __forceinline__ void xcd_wait(const XcdBarrier& b, unsigned use) {
;     if (b.w0 != 0 && lane_id() == 0) {
;         unsigned* bar = b.bar;
;         XB_SPIN(xb_ld(&bar[XB_TOPGEN]) <= use, bar);
;         __builtin_amdgcn_fence(__ATOMIC_ACQUIRE, "agent");
;         asm volatile("s_waitcnt vmcnt(0)" ::: "memory");
;     }
;     __syncthreads();
.LBB0_558:
	v_lshl_add_u32 v130, s6, 8, v128
	v_ashrrev_i32_e32 v131, 31, v130
	v_or_b32_e32 v132, s97, v129
	v_lshlrev_b64 v[128:129], 12, v[130:131]
	v_lshl_add_u64 v[128:129], s[2:3], 0, v[128:129]
	v_lshlrev_b32_e32 v224, 1, v132
	v_mov_b32_e32 v225, 0
	v_lshl_add_u64 v[128:129], v[128:129], 0, v[224:225]
	v_cvt_pk_bf16_f32 v120, v120, v121
	v_cvt_pk_bf16_f32 v121, v122, v123
	v_cvt_pk_bf16_f32 v122, v112, v113
	v_cvt_pk_bf16_f32 v123, v114, v115
	global_store_dwordx4 v[128:129], v[120:123], off
	v_cvt_pk_bf16_f32 v112, v124, v125
	v_cvt_pk_bf16_f32 v113, v126, v127
	v_cvt_pk_bf16_f32 v114, v116, v117
	v_cvt_pk_bf16_f32 v115, v118, v119
	global_store_dwordx4 v[128:129], v[112:115], off offset:256
	v_cvt_pk_bf16_f32 v104, v104, v105
	v_cvt_pk_bf16_f32 v105, v106, v107
	v_cvt_pk_bf16_f32 v106, v96, v97
	v_cvt_pk_bf16_f32 v107, v98, v99
	s_mov_b64 s[0:1], 0x80000
	s_nop 0
	v_or_b32_e32 v112, 16, v130
	v_ashrrev_i32_e32 v113, 31, v112
	v_lshlrev_b64 v[112:113], 12, v[112:113]
	v_lshl_add_u64 v[112:113], s[2:3], 0, v[112:113]
	v_lshl_add_u64 v[112:113], v[112:113], 0, v[224:225]
	global_store_dwordx4 v[112:113], v[104:107], off
	v_cvt_pk_bf16_f32 v96, v108, v109
	v_cvt_pk_bf16_f32 v97, v110, v111
	v_cvt_pk_bf16_f32 v98, v100, v101
	v_cvt_pk_bf16_f32 v99, v102, v103
	global_store_dwordx4 v[112:113], v[96:99], off offset:256
	v_cvt_pk_bf16_f32 v88, v88, v89
	v_cvt_pk_bf16_f32 v89, v90, v91
	v_cvt_pk_bf16_f32 v90, v80, v81
	v_cvt_pk_bf16_f32 v91, v82, v83
	s_mov_b32 s42, 0
	s_nop 0
	v_or_b32_e32 v96, 32, v130
	v_ashrrev_i32_e32 v97, 31, v96
	v_lshlrev_b64 v[96:97], 12, v[96:97]
	v_lshl_add_u64 v[96:97], s[2:3], 0, v[96:97]
	v_lshl_add_u64 v[96:97], v[96:97], 0, v[224:225]
	global_store_dwordx4 v[96:97], v[88:91], off
	v_cvt_pk_bf16_f32 v80, v92, v93
	v_cvt_pk_bf16_f32 v81, v94, v95
	v_cvt_pk_bf16_f32 v82, v84, v85
	v_cvt_pk_bf16_f32 v83, v86, v87
	global_store_dwordx4 v[96:97], v[80:83], off offset:256
	v_cvt_pk_bf16_f32 v56, v56, v57
	v_cvt_pk_bf16_f32 v57, v58, v59
	v_cvt_pk_bf16_f32 v58, v48, v49
	v_cvt_pk_bf16_f32 v59, v50, v51
	s_nop 1
	v_or_b32_e32 v80, 48, v130
	v_ashrrev_i32_e32 v81, 31, v80
	v_lshlrev_b64 v[80:81], 12, v[80:81]
	v_lshl_add_u64 v[80:81], s[2:3], 0, v[80:81]
	v_lshl_add_u64 v[80:81], v[80:81], 0, v[224:225]
	global_store_dwordx4 v[80:81], v[56:59], off
	v_cvt_pk_bf16_f32 v48, v60, v61
	v_cvt_pk_bf16_f32 v49, v62, v63
	v_cvt_pk_bf16_f32 v50, v52, v53
	v_lshl_add_u64 v[52:53], v[128:129], 0, s[0:1]
	s_mov_b32 s0, 0x80000
	v_cvt_pk_bf16_f32 v51, v54, v55
	v_add_co_u32_e32 v54, vcc, s0, v128
	global_store_dwordx4 v[80:81], v[48:51], off offset:256
	s_nop 0
	v_addc_co_u32_e32 v55, vcc, 0, v129, vcc
	v_cvt_pk_bf16_f32 v48, v76, v77
	v_cvt_pk_bf16_f32 v49, v78, v79
	v_cvt_pk_bf16_f32 v50, v72, v73
	v_cvt_pk_bf16_f32 v51, v74, v75
	global_store_dwordx4 v[54:55], v[48:51], off
	s_mov_b64 s[0:1], 0x90000
	s_nop 0
	v_cvt_pk_bf16_f32 v48, v68, v69
	v_cvt_pk_bf16_f32 v49, v70, v71
	v_cvt_pk_bf16_f32 v50, v64, v65
	v_cvt_pk_bf16_f32 v51, v66, v67
	global_store_dwordx4 v[52:53], v[48:51], off offset:256
	v_cvt_pk_bf16_f32 v44, v44, v45
	v_cvt_pk_bf16_f32 v45, v46, v47
	v_cvt_pk_bf16_f32 v46, v36, v37
	v_cvt_pk_bf16_f32 v47, v38, v39
	s_nop 1
	v_lshl_add_u64 v[48:49], v[128:129], 0, s[0:1]
	s_mov_b32 s0, 0x90000
	v_add_co_u32_e32 v36, vcc, s0, v128
	s_mov_b64 s[0:1], 0xa0000
	s_nop 0
	v_addc_co_u32_e32 v37, vcc, 0, v129, vcc
	global_store_dwordx4 v[36:37], v[44:47], off
	v_cvt_pk_bf16_f32 v36, v40, v41
	v_cvt_pk_bf16_f32 v37, v42, v43
	v_cvt_pk_bf16_f32 v38, v32, v33
	v_lshl_add_u64 v[32:33], v[128:129], 0, s[0:1]
	s_mov_b32 s0, 0xa0000
	v_cvt_pk_bf16_f32 v39, v34, v35
	global_store_dwordx4 v[48:49], v[36:39], off offset:256
	v_cvt_pk_bf16_f32 v28, v28, v29
	v_cvt_pk_bf16_f32 v29, v30, v31
	v_cvt_pk_bf16_f32 v30, v20, v21
	v_add_co_u32_e32 v20, vcc, s0, v128
	s_mov_b64 s[0:1], 0xb0000
	s_nop 0
	v_addc_co_u32_e32 v21, vcc, 0, v129, vcc
	v_cvt_pk_bf16_f32 v31, v22, v23
	global_store_dwordx4 v[20:21], v[28:31], off
	v_cvt_pk_bf16_f32 v20, v24, v25
	v_cvt_pk_bf16_f32 v21, v26, v27
	v_cvt_pk_bf16_f32 v22, v16, v17
	v_lshl_add_u64 v[16:17], v[128:129], 0, s[0:1]
	s_mov_b32 s0, 0xb0000
	v_cvt_pk_bf16_f32 v23, v18, v19
	global_store_dwordx4 v[32:33], v[20:23], off offset:256
	v_cvt_pk_bf16_f32 v12, v12, v13
	v_cvt_pk_bf16_f32 v13, v14, v15
	v_cvt_pk_bf16_f32 v14, v4, v5
	v_add_co_u32_e32 v4, vcc, s0, v128
	v_cvt_pk_bf16_f32 v15, v6, v7
	s_nop 1
	v_addc_co_u32_e32 v5, vcc, 0, v129, vcc
	global_store_dwordx4 v[4:5], v[12:15], off
	v_cvt_pk_bf16_f32 v4, v8, v9
	v_cvt_pk_bf16_f32 v5, v10, v11
	v_cvt_pk_bf16_f32 v6, v0, v1
	v_cvt_pk_bf16_f32 v7, v2, v3
	global_store_dwordx4 v[16:17], v[4:7], off offset:256
	s_and_b64 vcc, exec, s[94:95]
	s_cbranch_vccnz .Lfw3_skip
	s_mov_b64 s[6:7], exec
	v_mbcnt_lo_u32_b32 v0, -1, 0
	v_mbcnt_hi_u32_b32 v0, -1, v0
	v_cmp_eq_u32_e32 vcc, 0, v0
	s_and_b64 exec, exec, vcc
	v_readlane_b32 s16, v254, 19
	v_readlane_b32 s17, v254, 21
	s_add_i32 s16, s16, s17
	s_lshl_b32 s16, s16, 7
	s_add_u32 s16, s16, 0x7800
	v_mov_b32_e32 v0, s16
	global_load_dword v1, v0, s[52:53] sc1
	buffer_inv sc1
	s_mov_b64 exec, s[6:7]
.Lfw3_skip:
	s_waitcnt vmcnt(0)
	s_and_b64 vcc, exec, s[94:95]
	s_barrier
	s_cbranch_vccnz .LBB0_575
	v_mbcnt_lo_u32_b32 v0, -1, 0
	v_mbcnt_hi_u32_b32 v0, -1, v0
	s_nop 0
	v_cmp_eq_u32_e32 vcc, 0, v0
	s_and_saveexec_b64 s[0:1], vcc
	s_cbranch_execz .LBB0_574
	v_readlane_b32 s6, v254, 19
	v_readlane_b32 s7, v254, 21
	s_add_i32 s6, s6, s7
	s_lshl_b32 s6, s6, 7
	s_add_u32 s6, s6, 0x7800
	v_mov_b32_e32 v0, s6
	v_cmp_lt_u32_e32 vcc, 7, v1
	s_cbranch_vccnz .LBB0_574
	s_mov_b32 s13, 0x40000
